# RMSNorm phases (norm1 in phase 0, norm2): adaLN scale/shift quads loaded once per row pair before the first wait (were 14-16 late serialised loads, each also waiting for the previous store)
# speedup vs baseline: 1.0067x; 1.0042x over previous
.LBB0_253:
	v_ashrrev_i32_e32 v45, 31, v44
	v_lshlrev_b64 v[18:19], 12, v[44:45]
	v_lshl_add_u64 v[18:19], v[38:39], 0, v[18:19]
	v_lshlrev_b64 v[92:93], 11, v[44:45]
	global_load_dwordx4 v[34:37], v[18:19], off nt
	global_load_dwordx4 v[56:59], v[18:19], off offset:1024 nt
	global_load_dwordx4 v[76:79], v[18:19], off offset:2048 nt
	global_load_dwordx4 v[80:83], v[18:19], off offset:3072 nt
	v_lshl_add_u64 v[18:19], v[40:41], 0, v[92:93]
	global_load_dwordx2 v[70:71], v[18:19], off
	global_load_dwordx2 v[84:85], v[18:19], off offset:512
	global_load_dwordx2 v[86:87], v[18:19], off offset:1024
	global_load_dwordx2 v[94:95], v[18:19], off offset:1536
	v_ashrrev_i32_e32 v45, 10, v1
	v_mul_hi_i32_i24_e32 v69, 0x6000, v45
	v_mul_i32_i24_e32 v68, 0x6000, v45
	v_lshl_add_u64 v[68:69], s[6:7], 0, v[68:69]
	s_mov_b64 s[2:3], 0x4000
	v_lshl_add_u64 v[74:75], v[68:69], 0, s[2:3]
	s_mov_b64 s[2:3], 0x3000
	v_lshl_add_u64 v[72:73], v[68:69], 0, s[2:3]
	v_add_u32_e32 v54, 1, v44
	v_ashrrev_i32_e32 v55, 31, v54
	v_lshlrev_b64 v[18:19], 12, v[54:55]
	v_lshlrev_b64 v[54:55], 11, v[54:55]
	v_mov_b32_e32 v47, v0
	v_lshl_add_u64 v[18:19], v[38:39], 0, v[18:19]
	v_lshl_add_u64 v[60:61], v[40:41], 0, v[54:55]
	v_lshl_add_u64 v[68:69], v[74:75], 0, v[46:47]
	global_load_dwordx4 v[176:179], v[68:69], off
	global_load_dwordx4 v[180:183], v[68:69], off offset:1024
	global_load_dwordx4 v[184:187], v[68:69], off offset:2048
	global_load_dwordx4 v[188:191], v[68:69], off offset:3072
	v_lshl_add_u64 v[208:209], v[72:73], 0, v[46:47]
	global_load_dwordx4 v[192:195], v[208:209], off
	global_load_dwordx4 v[196:199], v[208:209], off offset:1024
	global_load_dwordx4 v[200:203], v[208:209], off offset:2048
	global_load_dwordx4 v[204:207], v[208:209], off offset:3072
	global_load_dwordx4 v[30:33], v[18:19], off nt
	global_load_dwordx4 v[26:29], v[18:19], off offset:1024 nt
	global_load_dwordx4 v[22:25], v[18:19], off offset:2048 nt
	s_nop 0
	global_load_dwordx4 v[18:21], v[18:19], off offset:3072 nt
	s_nop 0
	global_load_dwordx2 v[66:67], v[60:61], off
	global_load_dwordx2 v[64:65], v[60:61], off offset:512
	global_load_dwordx2 v[62:63], v[60:61], off offset:1024
	s_nop 0
	global_load_dwordx2 v[60:61], v[60:61], off offset:1536
	v_mov_b32_e32 v49, v0
	v_mov_b32_e32 v51, v0
	v_mov_b32_e32 v53, v0
	v_lshl_add_u64 v[54:55], v[42:43], 0, v[54:55]
	v_add_u32_e32 v1, s33, v1
	v_add_u32_e32 v44, s95, v44
	s_waitcnt vmcnt(0)
	v_lshlrev_b32_e32 v88, 16, v70
	v_and_b32_e32 v89, 0xffff0000, v70
	v_pk_add_f32 v[96:97], v[34:35], v[88:89]
	v_lshlrev_b32_e32 v34, 16, v71
	v_and_b32_e32 v35, 0xffff0000, v71
	v_pk_add_f32 v[98:99], v[36:37], v[34:35]
	v_mov_b32_e32 v36, v97
	v_mov_b32_e32 v37, v99
	v_mov_b32_e32 v34, v96
	v_mov_b32_e32 v35, v98
	v_pk_mul_f32 v[36:37], v[36:37], v[36:37]
	v_lshlrev_b32_e32 v70, 16, v94
	v_pk_fma_f32 v[34:35], v[34:35], v[34:35], v[36:37]
	v_lshlrev_b32_e32 v36, 16, v84
	v_and_b32_e32 v37, 0xffff0000, v84
	v_pk_add_f32 v[88:89], v[56:57], v[36:37]
	v_lshlrev_b32_e32 v36, 16, v85
	v_and_b32_e32 v37, 0xffff0000, v85
	v_pk_add_f32 v[90:91], v[58:59], v[36:37]
	v_mov_b32_e32 v56, v89
	v_mov_b32_e32 v57, v91
	v_mov_b32_e32 v36, v88
	v_mov_b32_e32 v37, v90
	v_pk_mul_f32 v[56:57], v[56:57], v[56:57]
	v_and_b32_e32 v71, 0xffff0000, v94
	v_pk_fma_f32 v[36:37], v[36:37], v[36:37], v[56:57]
	v_lshlrev_b32_e32 v56, 16, v86
	v_and_b32_e32 v57, 0xffff0000, v86
	v_pk_add_f32 v[84:85], v[76:77], v[56:57]
	v_lshlrev_b32_e32 v56, 16, v87
	v_and_b32_e32 v57, 0xffff0000, v87
	v_pk_add_f32 v[86:87], v[78:79], v[56:57]
	v_pk_add_f32 v[76:77], v[80:81], v[70:71]
	v_lshlrev_b32_e32 v70, 16, v95
	v_and_b32_e32 v71, 0xffff0000, v95
	v_mul_f32_e32 v56, v85, v85
	v_mul_f32_e32 v58, v87, v87
	v_pk_add_f32 v[78:79], v[82:83], v[70:71]
	v_pk_add_f32 v[34:35], v[34:35], v[34:35] op_sel:[0,1] op_sel_hi:[1,0]
	v_pk_add_f32 v[36:37], v[36:37], v[36:37] op_sel:[0,1] op_sel_hi:[1,0]
	v_pk_fma_f32 v[56:57], v[84:85], v[84:85], v[56:57] op_sel_hi:[1,1,0]
	v_pk_fma_f32 v[58:59], v[86:87], v[86:87], v[58:59] op_sel_hi:[1,1,0]
	v_pk_mul_f32 v[70:71], v[76:77], v[76:77]
	v_pk_mul_f32 v[80:81], v[78:79], v[78:79]
	v_mov_b32_e32 v35, v70
	v_mov_b32_e32 v37, v71
	v_mov_b32_e32 v57, v80
	v_mov_b32_e32 v59, v81
	v_pk_add_f32 v[34:35], v[34:35], v[36:37]
	v_pk_add_f32 v[36:37], v[56:57], v[58:59]
	v_lshl_add_u64 v[70:71], v[72:73], 0, v[46:47]
	v_pk_add_f32 v[34:35], v[34:35], v[36:37]
	v_mov_b64_e32 v[56:57], v[192:193]
	v_mov_b64_e32 v[58:59], v[194:195]
	v_add_f32_e32 v34, v34, v35
	s_nop 1
	v_add_f32_dpp v34, v34, v34 quad_perm:[1,0,3,2] row_mask:0xf bank_mask:0xf bound_ctrl:1
	s_nop 1
	v_add_f32_dpp v34, v34, v34 quad_perm:[2,3,0,1] row_mask:0xf bank_mask:0xf bound_ctrl:1
	s_nop 1
	v_add_f32_dpp v34, v34, v34 row_half_mirror row_mask:0xf bank_mask:0xf bound_ctrl:1
	s_nop 1
	v_add_f32_dpp v34, v34, v34 row_mirror row_mask:0xf bank_mask:0xf bound_ctrl:1
	s_nop 0
	v_readlane_b32 s8, v34, 16
	v_readlane_b32 s9, v34, 48
	v_readlane_b32 s2, v34, 0
	v_readlane_b32 s3, v34, 32
	v_mov_b32_e32 v34, s8
	v_mov_b32_e32 v35, s9
	v_pk_add_f32 v[34:35], s[2:3], v[34:35]
	s_nop 0
	v_add_f32_e32 v34, v34, v35
	v_fmamk_f32 v34, v34, 0x3a800000, v162
	v_cmp_gt_f32_e32 vcc, s82, v34
	v_mul_f32_e32 v35, 0x4b800000, v34
	s_nop 0
	v_cndmask_b32_e32 v34, v34, v35, vcc
	v_rsq_f32_e32 v34, v34
	s_nop 0
	v_mul_f32_e32 v35, 0x45800000, v34
	v_cndmask_b32_e32 v80, v34, v35, vcc
	v_mov_b64_e32 v[34:35], v[176:177]
	v_mov_b64_e32 v[36:37], v[178:179]
	v_pk_mul_f32 v[82:83], v[98:99], v[80:81] op_sel_hi:[1,0]
	v_pk_mul_f32 v[94:95], v[96:97], v[80:81] op_sel_hi:[1,0]
	v_pk_mul_f32 v[82:83], v[4:5], v[82:83]
	v_pk_mul_f32 v[94:95], v[2:3], v[94:95]
	v_pk_mul_f32 v[88:89], v[88:89], v[80:81] op_sel_hi:[1,0]
	v_pk_mul_f32 v[90:91], v[90:91], v[80:81] op_sel_hi:[1,0]
	v_pk_mul_f32 v[88:89], v[6:7], v[88:89]
	v_pk_mul_f32 v[90:91], v[8:9], v[90:91]
	v_pk_mul_f32 v[84:85], v[84:85], v[80:81] op_sel_hi:[1,0]
	v_pk_mul_f32 v[86:87], v[86:87], v[80:81] op_sel_hi:[1,0]
	v_pk_mul_f32 v[84:85], v[10:11], v[84:85]
	v_pk_mul_f32 v[86:87], v[12:13], v[86:87]
	v_pk_mul_f32 v[76:77], v[76:77], v[80:81] op_sel_hi:[1,0]
	v_pk_mul_f32 v[78:79], v[78:79], v[80:81] op_sel_hi:[1,0]
	v_pk_mul_f32 v[76:77], v[14:15], v[76:77]
	v_pk_mul_f32 v[78:79], v[16:17], v[78:79]
	v_pk_add_f32 v[36:37], v[36:37], 1.0 op_sel_hi:[1,0]
	v_pk_add_f32 v[34:35], v[34:35], 1.0 op_sel_hi:[1,0]
	v_pk_fma_f32 v[36:37], v[36:37], v[82:83], v[58:59]
	v_pk_fma_f32 v[34:35], v[34:35], v[94:95], v[56:57]
	v_lshl_add_u64 v[82:83], v[42:43], 0, v[92:93]
	v_cvt_pk_bf16_f32 v34, v34, v35
	v_cvt_pk_bf16_f32 v35, v36, v37
	global_store_dwordx2 v[82:83], v[34:35], off
	v_lshl_add_u64 v[56:57], v[74:75], 0, v[48:49]
	v_mov_b64_e32 v[34:35], v[180:181]
	v_mov_b64_e32 v[36:37], v[182:183]
	v_lshl_add_u64 v[58:59], v[72:73], 0, v[48:49]
	v_mov_b64_e32 v[92:93], v[196:197]
	v_mov_b64_e32 v[94:95], v[198:199]
	v_pk_add_f32 v[34:35], v[34:35], 1.0 op_sel_hi:[1,0]
	v_pk_add_f32 v[36:37], v[36:37], 1.0 op_sel_hi:[1,0]
	v_pk_fma_f32 v[34:35], v[34:35], v[88:89], v[92:93]
	v_pk_fma_f32 v[36:37], v[36:37], v[90:91], v[94:95]
	v_cvt_pk_bf16_f32 v34, v34, v35
	s_nop 0
	v_cvt_pk_bf16_f32 v35, v36, v37
	global_store_dwordx2 v[82:83], v[34:35], off offset:512
	v_lshl_add_u64 v[34:35], v[74:75], 0, v[50:51]
	v_mov_b64_e32 v[88:89], v[184:185]
	v_mov_b64_e32 v[90:91], v[186:187]
	v_lshl_add_u64 v[36:37], v[72:73], 0, v[50:51]
	v_mov_b64_e32 v[92:93], v[200:201]
	v_mov_b64_e32 v[94:95], v[202:203]
	v_lshl_add_u64 v[74:75], v[74:75], 0, v[52:53]
	v_lshl_add_u64 v[72:73], v[72:73], 0, v[52:53]
	v_pk_add_f32 v[88:89], v[88:89], 1.0 op_sel_hi:[1,0]
	v_pk_add_f32 v[90:91], v[90:91], 1.0 op_sel_hi:[1,0]
	v_pk_fma_f32 v[84:85], v[88:89], v[84:85], v[92:93]
	v_pk_fma_f32 v[86:87], v[90:91], v[86:87], v[94:95]
	v_cvt_pk_bf16_f32 v84, v84, v85
	s_nop 0
	v_cvt_pk_bf16_f32 v85, v86, v87
	global_store_dwordx2 v[82:83], v[84:85], off offset:1024
	v_mov_b64_e32 v[84:85], v[188:189]
	v_mov_b64_e32 v[86:87], v[190:191]
	s_nop 0
	v_mov_b64_e32 v[88:89], v[204:205]
	v_mov_b64_e32 v[90:91], v[206:207]
	v_pk_add_f32 v[84:85], v[84:85], 1.0 op_sel_hi:[1,0]
	v_pk_add_f32 v[80:81], v[86:87], 1.0 op_sel_hi:[1,0]
	v_pk_fma_f32 v[76:77], v[76:77], v[84:85], v[88:89]
	v_pk_fma_f32 v[78:79], v[78:79], v[80:81], v[90:91]
	v_cvt_pk_bf16_f32 v76, v76, v77
	s_nop 0
	v_cvt_pk_bf16_f32 v77, v78, v79
	global_store_dwordx2 v[82:83], v[76:77], off offset:1536
	v_lshlrev_b32_e32 v76, 16, v66
	v_and_b32_e32 v77, 0xffff0000, v66
	v_pk_add_f32 v[76:77], v[30:31], v[76:77]
	v_lshlrev_b32_e32 v30, 16, v67
	v_and_b32_e32 v31, 0xffff0000, v67
	v_pk_add_f32 v[32:33], v[32:33], v[30:31]
	v_mov_b32_e32 v66, v77
	v_mov_b32_e32 v67, v33
	v_mov_b32_e32 v30, v76
	v_mov_b32_e32 v31, v32
	v_pk_mul_f32 v[66:67], v[66:67], v[66:67]
	v_lshlrev_b32_e32 v78, 16, v60
	v_pk_fma_f32 v[30:31], v[30:31], v[30:31], v[66:67]
	v_lshlrev_b32_e32 v66, 16, v64
	v_and_b32_e32 v67, 0xffff0000, v64
	v_lshlrev_b32_e32 v64, 16, v65
	v_and_b32_e32 v65, 0xffff0000, v65
	v_pk_add_f32 v[26:27], v[26:27], v[66:67]
	v_pk_add_f32 v[28:29], v[28:29], v[64:65]
	v_mov_b32_e32 v66, v27
	v_mov_b32_e32 v67, v29
	v_mov_b32_e32 v64, v26
	v_mov_b32_e32 v65, v28
	v_pk_mul_f32 v[66:67], v[66:67], v[66:67]
	v_and_b32_e32 v79, 0xffff0000, v60
	v_pk_fma_f32 v[64:65], v[64:65], v[64:65], v[66:67]
	v_lshlrev_b32_e32 v66, 16, v62
	v_and_b32_e32 v67, 0xffff0000, v62
	v_lshlrev_b32_e32 v62, 16, v63
	v_and_b32_e32 v63, 0xffff0000, v63
	v_pk_add_f32 v[22:23], v[22:23], v[66:67]
	v_pk_add_f32 v[24:25], v[24:25], v[62:63]
	v_lshlrev_b32_e32 v60, 16, v61
	v_and_b32_e32 v61, 0xffff0000, v61
	v_mul_f32_e32 v62, v23, v23
	v_mul_f32_e32 v66, v25, v25
	v_pk_add_f32 v[18:19], v[18:19], v[78:79]
	v_pk_add_f32 v[20:21], v[20:21], v[60:61]
	v_pk_add_f32 v[30:31], v[30:31], v[30:31] op_sel:[0,1] op_sel_hi:[1,0]
	v_pk_add_f32 v[64:65], v[64:65], v[64:65] op_sel:[0,1] op_sel_hi:[1,0]
	v_pk_fma_f32 v[62:63], v[22:23], v[22:23], v[62:63] op_sel_hi:[1,1,0]
	v_pk_fma_f32 v[66:67], v[24:25], v[24:25], v[66:67] op_sel_hi:[1,1,0]
	v_pk_mul_f32 v[60:61], v[18:19], v[18:19]
	v_pk_mul_f32 v[78:79], v[20:21], v[20:21]
	v_mov_b32_e32 v31, v60
	v_mov_b32_e32 v65, v61
	v_mov_b32_e32 v63, v78
	v_mov_b32_e32 v67, v79
	v_pk_add_f32 v[30:31], v[30:31], v[64:65]
	v_pk_add_f32 v[60:61], v[62:63], v[66:67]
	s_nop 0
	v_pk_add_f32 v[30:31], v[30:31], v[60:61]
	v_mov_b64_e32 v[60:61], v[176:177]
	v_mov_b64_e32 v[62:63], v[178:179]
	v_mov_b64_e32 v[64:65], v[192:193]
	v_mov_b64_e32 v[66:67], v[194:195]
	v_add_f32_e32 v30, v30, v31
	v_pk_add_f32 v[62:63], v[62:63], 1.0 op_sel_hi:[1,0]
	v_add_f32_dpp v30, v30, v30 quad_perm:[1,0,3,2] row_mask:0xf bank_mask:0xf bound_ctrl:1
	v_pk_add_f32 v[60:61], v[60:61], 1.0 op_sel_hi:[1,0]
	s_nop 0
	v_add_f32_dpp v30, v30, v30 quad_perm:[2,3,0,1] row_mask:0xf bank_mask:0xf bound_ctrl:1
	s_nop 1
	v_add_f32_dpp v30, v30, v30 row_half_mirror row_mask:0xf bank_mask:0xf bound_ctrl:1
	s_nop 1
	v_add_f32_dpp v30, v30, v30 row_mirror row_mask:0xf bank_mask:0xf bound_ctrl:1
	s_nop 0
	v_readlane_b32 s8, v30, 16
	v_readlane_b32 s9, v30, 48
	v_readlane_b32 s2, v30, 0
	v_readlane_b32 s3, v30, 32
	v_mov_b32_e32 v30, s8
	v_mov_b32_e32 v31, s9
	v_pk_add_f32 v[30:31], s[2:3], v[30:31]
	s_nop 0
	v_add_f32_e32 v30, v30, v31
	v_fmamk_f32 v30, v30, 0x3a800000, v162
	v_cmp_gt_f32_e32 vcc, s82, v30
	v_mul_f32_e32 v31, 0x4b800000, v30
	s_nop 0
	v_cndmask_b32_e32 v30, v30, v31, vcc
	v_rsq_f32_e32 v30, v30
	s_nop 0
	v_mul_f32_e32 v31, 0x45800000, v30
	v_cndmask_b32_e32 v30, v30, v31, vcc
	v_pk_mul_f32 v[32:33], v[32:33], v[30:31] op_sel_hi:[1,0]
	v_pk_mul_f32 v[68:69], v[76:77], v[30:31] op_sel_hi:[1,0]
	v_pk_mul_f32 v[32:33], v[4:5], v[32:33]
	v_pk_mul_f32 v[68:69], v[2:3], v[68:69]
	v_pk_fma_f32 v[62:63], v[62:63], v[32:33], v[66:67]
	v_pk_fma_f32 v[32:33], v[60:61], v[68:69], v[64:65]
	v_pk_mul_f32 v[26:27], v[26:27], v[30:31] op_sel_hi:[1,0]
	v_cvt_pk_bf16_f32 v32, v32, v33
	v_cvt_pk_bf16_f32 v33, v62, v63
	global_store_dwordx2 v[54:55], v[32:33], off
	v_mov_b64_e32 v[60:61], v[180:181]
	v_mov_b64_e32 v[62:63], v[182:183]
	s_nop 0
	v_mov_b64_e32 v[56:57], v[196:197]
	v_mov_b64_e32 v[58:59], v[198:199]
	v_pk_mul_f32 v[28:29], v[28:29], v[30:31] op_sel_hi:[1,0]
	v_pk_mul_f32 v[26:27], v[6:7], v[26:27]
	v_pk_mul_f32 v[28:29], v[8:9], v[28:29]
	v_pk_mul_f32 v[22:23], v[22:23], v[30:31] op_sel_hi:[1,0]
	v_pk_mul_f32 v[24:25], v[24:25], v[30:31] op_sel_hi:[1,0]
	v_pk_mul_f32 v[22:23], v[10:11], v[22:23]
	v_pk_mul_f32 v[24:25], v[12:13], v[24:25]
	v_pk_mul_f32 v[18:19], v[18:19], v[30:31] op_sel_hi:[1,0]
	v_pk_mul_f32 v[20:21], v[20:21], v[30:31] op_sel_hi:[1,0]
	v_pk_mul_f32 v[18:19], v[14:15], v[18:19]
	v_cmp_lt_i32_e32 vcc, s34, v1
	v_pk_mul_f32 v[20:21], v[16:17], v[20:21]
	s_or_b64 s[12:13], vcc, s[12:13]
	v_pk_add_f32 v[60:61], v[60:61], 1.0 op_sel_hi:[1,0]
	v_pk_add_f32 v[32:33], v[62:63], 1.0 op_sel_hi:[1,0]
	v_pk_fma_f32 v[26:27], v[60:61], v[26:27], v[56:57]
	v_pk_fma_f32 v[28:29], v[32:33], v[28:29], v[58:59]
	v_cvt_pk_bf16_f32 v26, v26, v27
	s_nop 0
	v_cvt_pk_bf16_f32 v27, v28, v29
	global_store_dwordx2 v[54:55], v[26:27], off offset:512
	v_mov_b64_e32 v[26:27], v[184:185]
	v_mov_b64_e32 v[28:29], v[186:187]
	s_nop 0
	v_mov_b64_e32 v[32:33], v[200:201]
	v_mov_b64_e32 v[34:35], v[202:203]
	v_pk_add_f32 v[26:27], v[26:27], 1.0 op_sel_hi:[1,0]
	v_pk_add_f32 v[28:29], v[28:29], 1.0 op_sel_hi:[1,0]
	v_pk_fma_f32 v[22:23], v[26:27], v[22:23], v[32:33]
	v_pk_fma_f32 v[24:25], v[28:29], v[24:25], v[34:35]
	v_cvt_pk_bf16_f32 v22, v22, v23
	s_nop 0
	v_cvt_pk_bf16_f32 v23, v24, v25
	global_store_dwordx2 v[54:55], v[22:23], off offset:1024
	v_mov_b64_e32 v[22:23], v[188:189]
	v_mov_b64_e32 v[24:25], v[190:191]
	s_nop 0
	v_mov_b64_e32 v[26:27], v[204:205]
	v_mov_b64_e32 v[28:29], v[206:207]
	v_pk_add_f32 v[22:23], v[22:23], 1.0 op_sel_hi:[1,0]
	v_pk_add_f32 v[24:25], v[24:25], 1.0 op_sel_hi:[1,0]
	v_pk_fma_f32 v[18:19], v[18:19], v[22:23], v[26:27]
	v_pk_fma_f32 v[20:21], v[20:21], v[24:25], v[28:29]
	v_cvt_pk_bf16_f32 v18, v18, v19
	s_nop 0
	v_cvt_pk_bf16_f32 v19, v20, v21
	global_store_dwordx2 v[54:55], v[18:19], off offset:1536
	s_andn2_b64 exec, exec, s[12:13]
	s_cbranch_execnz .LBB0_253

.LBB0_508:
	v_ashrrev_i32_e32 v51, 31, v50
	v_lshlrev_b64 v[18:19], 12, v[50:51]
	v_lshl_add_u64 v[18:19], v[46:47], 0, v[18:19]
	global_load_dwordx4 v[74:77], v[18:19], off nt
	global_load_dwordx4 v[42:45], v[18:19], off offset:1024 nt
	global_load_dwordx4 v[38:41], v[18:19], off offset:2048 nt
	global_load_dwordx4 v[34:37], v[18:19], off offset:3072 nt
	v_ashrrev_i32_e32 v53, 10, v1
	v_add_u32_e32 v66, 1, v50
	v_mul_hi_i32_i24_e32 v61, 0x6000, v53
	v_mul_i32_i24_e32 v60, 0x6000, v53
	v_ashrrev_i32_e32 v67, 31, v66
	v_lshl_add_u64 v[60:61], s[6:7], 0, v[60:61]
	s_mov_b64 s[2:3], 0x1000
	v_lshlrev_b64 v[18:19], 12, v[66:67]
	v_lshl_add_u64 v[68:69], v[60:61], 0, s[2:3]
	v_mov_b32_e32 v53, v0
	v_lshl_add_u64 v[18:19], v[46:47], 0, v[18:19]
	v_lshl_add_u64 v[62:63], v[68:69], 0, v[52:53]
	global_load_dwordx4 v[30:33], v[18:19], off nt
	global_load_dwordx4 v[26:29], v[18:19], off offset:1024 nt
	global_load_dwordx4 v[22:25], v[18:19], off offset:2048 nt
	s_nop 0
	global_load_dwordx4 v[18:21], v[18:19], off offset:3072 nt
	v_lshl_add_u64 v[60:61], v[60:61], 0, v[52:53]
	v_add_u32_e32 v1, s33, v1
	global_load_dwordx4 v[82:85], v[60:61], off
	s_waitcnt vmcnt(8)
	v_pk_mul_f32 v[64:65], v[76:77], v[76:77]
	v_pk_mul_f32 v[70:71], v[74:75], v[74:75]
	s_waitcnt vmcnt(5)
	v_mul_f32_e32 v55, v34, v34
	v_pk_mov_b32 v[72:73], v[70:71], v[64:65] op_sel:[1,0]
	v_mov_b32_e32 v71, v65
	v_pk_add_f32 v[64:65], v[72:73], v[70:71]
	v_pk_mul_f32 v[70:71], v[44:45], v[44:45]
	v_pk_mul_f32 v[72:73], v[42:43], v[42:43]
	v_mul_f32_e32 v57, v35, v35
	v_pk_mov_b32 v[78:79], v[72:73], v[70:71] op_sel:[1,0]
	v_mov_b32_e32 v73, v71
	v_pk_add_f32 v[70:71], v[78:79], v[72:73]
	v_mul_f32_e32 v72, v41, v41
	v_mul_f32_e32 v78, v37, v37
	v_pk_fma_f32 v[72:73], v[40:41], v[40:41], v[72:73] op_sel_hi:[1,1,0]
	v_pk_add_f32 v[64:65], v[64:65], v[64:65] op_sel:[0,1] op_sel_hi:[1,0]
	v_mov_b32_e32 v73, v78
	global_load_dwordx4 v[78:81], v[62:63], off
	global_load_dwordx4 v[176:179], v[62:63], off
	global_load_dwordx4 v[180:183], v[62:63], off offset:1024
	global_load_dwordx4 v[184:187], v[62:63], off offset:2048
	global_load_dwordx4 v[188:191], v[62:63], off offset:3072
	global_load_dwordx4 v[192:195], v[60:61], off
	global_load_dwordx4 v[196:199], v[60:61], off offset:1024
	global_load_dwordx4 v[200:203], v[60:61], off offset:2048
	global_load_dwordx4 v[204:207], v[60:61], off offset:3072
	v_pk_add_f32 v[70:71], v[70:71], v[70:71] op_sel:[0,1] op_sel_hi:[1,0]
	v_mov_b32_e32 v65, v55
	v_mov_b32_e32 v71, v57
	v_pk_add_f32 v[64:65], v[64:65], v[70:71]
	v_mul_f32_e32 v70, v39, v39
	v_mul_f32_e32 v59, v36, v36
	v_pk_fma_f32 v[70:71], v[38:39], v[38:39], v[70:71] op_sel_hi:[1,1,0]
	s_waitcnt vmcnt(0)
	v_pk_add_f32 v[78:79], v[78:79], 1.0 op_sel_hi:[1,0]
	v_mov_b32_e32 v71, v59
	v_pk_add_f32 v[70:71], v[70:71], v[72:73]
	v_mov_b32_e32 v59, v0
	v_pk_add_f32 v[64:65], v[64:65], v[70:71]
	s_nop 0
	v_add_f32_e32 v55, v64, v65
	s_nop 1
	v_add_f32_dpp v55, v55, v55 quad_perm:[1,0,3,2] row_mask:0xf bank_mask:0xf bound_ctrl:1
	s_nop 1
	v_add_f32_dpp v55, v55, v55 quad_perm:[2,3,0,1] row_mask:0xf bank_mask:0xf bound_ctrl:1
	s_nop 1
	v_add_f32_dpp v55, v55, v55 row_half_mirror row_mask:0xf bank_mask:0xf bound_ctrl:1
	s_nop 1
	v_add_f32_dpp v55, v55, v55 row_mirror row_mask:0xf bank_mask:0xf bound_ctrl:1
	s_nop 0
	v_readlane_b32 s8, v55, 16
	v_readlane_b32 s9, v55, 48
	v_readlane_b32 s2, v55, 0
	v_readlane_b32 s3, v55, 32
	v_mov_b32_e32 v64, s8
	v_mov_b32_e32 v65, s9
	v_pk_add_f32 v[64:65], s[2:3], v[64:65]
	s_nop 0
	v_add_f32_e32 v55, v64, v65
	v_fmamk_f32 v55, v55, 0x3a800000, v162
	v_cmp_gt_f32_e32 vcc, s82, v55
	v_mul_f32_e32 v57, 0x4b800000, v55
	v_lshlrev_b64 v[64:65], 11, v[50:51]
	v_cndmask_b32_e32 v55, v55, v57, vcc
	v_rsq_f32_e32 v55, v55
	v_add_u32_e32 v50, s95, v50
	v_mul_f32_e32 v57, 0x45800000, v55
	v_cndmask_b32_e32 v72, v55, v57, vcc
	v_pk_mul_f32 v[70:71], v[76:77], v[72:73] op_sel_hi:[1,0]
	v_pk_mul_f32 v[74:75], v[74:75], v[72:73] op_sel_hi:[1,0]
	v_pk_mul_f32 v[70:71], v[4:5], v[70:71]
	v_pk_mul_f32 v[74:75], v[2:3], v[74:75]
	v_pk_add_f32 v[76:77], v[80:81], 1.0 op_sel_hi:[1,0]
	v_pk_fma_f32 v[74:75], v[78:79], v[74:75], v[82:83]
	v_pk_fma_f32 v[70:71], v[76:77], v[70:71], v[84:85]
	v_cvt_pk_bf16_f32 v74, v74, v75
	v_mov_b32_e32 v55, v0
	v_cvt_pk_bf16_f32 v75, v70, v71
	v_lshl_add_u64 v[70:71], v[48:49], 0, v[64:65]
	global_store_dwordx2 v[70:71], v[74:75], off
	v_lshl_add_u64 v[64:65], v[68:69], 0, v[54:55]
	v_mov_b64_e32 v[74:75], v[180:181]
	v_mov_b64_e32 v[76:77], v[182:183]
	v_mov_b64_e32 v[78:79], v[196:197]
	v_mov_b64_e32 v[80:81], v[198:199]
	v_pk_mul_f32 v[42:43], v[42:43], v[72:73] op_sel_hi:[1,0]
	v_pk_mul_f32 v[44:45], v[44:45], v[72:73] op_sel_hi:[1,0]
	v_pk_mul_f32 v[42:43], v[6:7], v[42:43]
	v_pk_mul_f32 v[44:45], v[8:9], v[44:45]
	v_mov_b32_e32 v57, v0
	v_pk_mul_f32 v[38:39], v[38:39], v[72:73] op_sel_hi:[1,0]
	v_pk_mul_f32 v[40:41], v[40:41], v[72:73] op_sel_hi:[1,0]
	v_pk_mul_f32 v[38:39], v[10:11], v[38:39]
	v_pk_mul_f32 v[40:41], v[12:13], v[40:41]
	v_pk_mul_f32 v[34:35], v[34:35], v[72:73] op_sel_hi:[1,0]
	v_pk_mul_f32 v[36:37], v[36:37], v[72:73] op_sel_hi:[1,0]
	v_pk_mul_f32 v[34:35], v[14:15], v[34:35]
	v_pk_mul_f32 v[36:37], v[16:17], v[36:37]
	v_pk_add_f32 v[74:75], v[74:75], 1.0 op_sel_hi:[1,0]
	v_pk_add_f32 v[76:77], v[76:77], 1.0 op_sel_hi:[1,0]
	v_pk_fma_f32 v[42:43], v[74:75], v[42:43], v[78:79]
	v_pk_fma_f32 v[44:45], v[76:77], v[44:45], v[80:81]
	v_cvt_pk_bf16_f32 v42, v42, v43
	s_nop 0
	v_cvt_pk_bf16_f32 v43, v44, v45
	global_store_dwordx2 v[70:71], v[42:43], off offset:512
	v_lshl_add_u64 v[42:43], v[68:69], 0, v[56:57]
	v_mov_b64_e32 v[74:75], v[184:185]
	v_mov_b64_e32 v[76:77], v[186:187]
	v_mov_b64_e32 v[78:79], v[200:201]
	v_mov_b64_e32 v[80:81], v[202:203]
	v_pk_add_f32 v[74:75], v[74:75], 1.0 op_sel_hi:[1,0]
	v_pk_add_f32 v[44:45], v[76:77], 1.0 op_sel_hi:[1,0]
	v_pk_fma_f32 v[38:39], v[74:75], v[38:39], v[78:79]
	v_pk_fma_f32 v[40:41], v[44:45], v[40:41], v[80:81]
	v_cvt_pk_bf16_f32 v38, v38, v39
	s_nop 0
	v_cvt_pk_bf16_f32 v39, v40, v41
	global_store_dwordx2 v[70:71], v[38:39], off offset:1024
	v_lshl_add_u64 v[38:39], v[68:69], 0, v[58:59]
	v_mov_b64_e32 v[74:75], v[188:189]
	v_mov_b64_e32 v[76:77], v[190:191]
	v_mov_b64_e32 v[78:79], v[204:205]
	v_mov_b64_e32 v[80:81], v[206:207]
	v_pk_add_f32 v[44:45], v[74:75], 1.0 op_sel_hi:[1,0]
	v_pk_add_f32 v[40:41], v[76:77], 1.0 op_sel_hi:[1,0]
	v_pk_fma_f32 v[34:35], v[34:35], v[44:45], v[78:79]
	v_pk_fma_f32 v[36:37], v[36:37], v[40:41], v[80:81]
	v_cvt_pk_bf16_f32 v34, v34, v35
	s_nop 0
	v_cvt_pk_bf16_f32 v35, v36, v37
	global_store_dwordx2 v[70:71], v[34:35], off offset:1536
	v_pk_mul_f32 v[34:35], v[32:33], v[32:33]
	v_pk_mul_f32 v[36:37], v[30:31], v[30:31]
	s_nop 0
	v_pk_mov_b32 v[40:41], v[36:37], v[34:35] op_sel:[1,0]
	v_mov_b32_e32 v37, v35
	v_pk_add_f32 v[34:35], v[40:41], v[36:37]
	v_pk_mul_f32 v[36:37], v[28:29], v[28:29]
	v_pk_mul_f32 v[40:41], v[26:27], v[26:27]
	v_pk_add_f32 v[34:35], v[34:35], v[34:35] op_sel:[0,1] op_sel_hi:[1,0]
	v_pk_mov_b32 v[44:45], v[40:41], v[36:37] op_sel:[1,0]
	v_mov_b32_e32 v41, v37
	v_pk_add_f32 v[36:37], v[44:45], v[40:41]
	v_mul_f32_e32 v40, v18, v18
	v_mul_f32_e32 v41, v19, v19
	v_pk_add_f32 v[36:37], v[36:37], v[36:37] op_sel:[0,1] op_sel_hi:[1,0]
	v_mov_b32_e32 v35, v40
	v_mov_b32_e32 v37, v41
	v_pk_add_f32 v[34:35], v[34:35], v[36:37]
	v_mul_f32_e32 v36, v23, v23
	v_mul_f32_e32 v40, v25, v25
	v_mul_f32_e32 v44, v20, v20
	v_mul_f32_e32 v45, v21, v21
	v_pk_fma_f32 v[36:37], v[22:23], v[22:23], v[36:37] op_sel_hi:[1,1,0]
	v_pk_fma_f32 v[40:41], v[24:25], v[24:25], v[40:41] op_sel_hi:[1,1,0]
	v_mov_b32_e32 v37, v44
	v_mov_b32_e32 v41, v45
	v_pk_add_f32 v[36:37], v[36:37], v[40:41]
	s_nop 0
	v_pk_add_f32 v[34:35], v[34:35], v[36:37]
	v_lshlrev_b64 v[36:37], 11, v[66:67]
	v_mov_b64_e32 v[66:67], v[176:177]
	v_mov_b64_e32 v[68:69], v[178:179]
	v_mov_b64_e32 v[70:71], v[192:193]
	v_mov_b64_e32 v[72:73], v[194:195]
	v_add_f32_e32 v34, v34, v35
	v_pk_add_f32 v[44:45], v[66:67], 1.0 op_sel_hi:[1,0]
	v_add_f32_dpp v34, v34, v34 quad_perm:[1,0,3,2] row_mask:0xf bank_mask:0xf bound_ctrl:1
	v_pk_add_f32 v[40:41], v[68:69], 1.0 op_sel_hi:[1,0]
	s_nop 0
	v_add_f32_dpp v34, v34, v34 quad_perm:[2,3,0,1] row_mask:0xf bank_mask:0xf bound_ctrl:1
	s_nop 1
	v_add_f32_dpp v34, v34, v34 row_half_mirror row_mask:0xf bank_mask:0xf bound_ctrl:1
	s_nop 1
	v_add_f32_dpp v34, v34, v34 row_mirror row_mask:0xf bank_mask:0xf bound_ctrl:1
	s_nop 0
	v_readlane_b32 s8, v34, 16
	v_readlane_b32 s9, v34, 48
	v_readlane_b32 s2, v34, 0
	v_readlane_b32 s3, v34, 32
	v_mov_b32_e32 v34, s8
	v_mov_b32_e32 v35, s9
	v_pk_add_f32 v[34:35], s[2:3], v[34:35]
	s_nop 0
	v_add_f32_e32 v34, v34, v35
	v_fmamk_f32 v34, v34, 0x3a800000, v162
	v_cmp_gt_f32_e32 vcc, s82, v34
	v_mul_f32_e32 v35, 0x4b800000, v34
	s_nop 0
	v_cndmask_b32_e32 v34, v34, v35, vcc
	v_rsq_f32_e32 v34, v34
	s_nop 0
	v_mul_f32_e32 v35, 0x45800000, v34
	v_cndmask_b32_e32 v34, v34, v35, vcc
	v_pk_mul_f32 v[30:31], v[30:31], v[34:35] op_sel_hi:[1,0]
	v_pk_mul_f32 v[32:33], v[32:33], v[34:35] op_sel_hi:[1,0]
	v_pk_mul_f32 v[30:31], v[2:3], v[30:31]
	v_pk_mul_f32 v[32:33], v[4:5], v[32:33]
	v_pk_fma_f32 v[30:31], v[44:45], v[30:31], v[70:71]
	v_pk_fma_f32 v[40:41], v[40:41], v[32:33], v[72:73]
	v_cvt_pk_bf16_f32 v32, v30, v31
	v_lshl_add_u64 v[30:31], v[48:49], 0, v[36:37]
	v_cvt_pk_bf16_f32 v33, v40, v41
	global_store_dwordx2 v[30:31], v[32:33], off
	v_mov_b64_e32 v[62:63], v[180:181]
	v_mov_b64_e32 v[64:65], v[182:183]
	s_nop 0
	v_mov_b64_e32 v[66:67], v[196:197]
	v_mov_b64_e32 v[68:69], v[198:199]
	v_pk_mul_f32 v[26:27], v[26:27], v[34:35] op_sel_hi:[1,0]
	v_pk_mul_f32 v[28:29], v[28:29], v[34:35] op_sel_hi:[1,0]
	v_pk_mul_f32 v[26:27], v[6:7], v[26:27]
	v_pk_mul_f32 v[28:29], v[8:9], v[28:29]
	v_pk_mul_f32 v[22:23], v[22:23], v[34:35] op_sel_hi:[1,0]
	v_pk_mul_f32 v[24:25], v[24:25], v[34:35] op_sel_hi:[1,0]
	v_pk_mul_f32 v[22:23], v[10:11], v[22:23]
	v_pk_mul_f32 v[24:25], v[12:13], v[24:25]
	v_pk_mul_f32 v[18:19], v[18:19], v[34:35] op_sel_hi:[1,0]
	v_pk_mul_f32 v[20:21], v[20:21], v[34:35] op_sel_hi:[1,0]
	v_pk_mul_f32 v[18:19], v[14:15], v[18:19]
	v_cmp_lt_i32_e32 vcc, s34, v1
	v_pk_mul_f32 v[20:21], v[16:17], v[20:21]
	s_or_b64 s[0:1], vcc, s[0:1]
	v_pk_add_f32 v[36:37], v[62:63], 1.0 op_sel_hi:[1,0]
	v_pk_add_f32 v[32:33], v[64:65], 1.0 op_sel_hi:[1,0]
	v_pk_fma_f32 v[26:27], v[36:37], v[26:27], v[66:67]
	v_pk_fma_f32 v[28:29], v[32:33], v[28:29], v[68:69]
	v_cvt_pk_bf16_f32 v26, v26, v27
	s_nop 0
	v_cvt_pk_bf16_f32 v27, v28, v29
	global_store_dwordx2 v[30:31], v[26:27], off offset:512
	v_mov_b64_e32 v[26:27], v[184:185]
	v_mov_b64_e32 v[28:29], v[186:187]
	s_nop 0
	v_mov_b64_e32 v[40:41], v[200:201]
	v_mov_b64_e32 v[42:43], v[202:203]
	v_pk_add_f32 v[26:27], v[26:27], 1.0 op_sel_hi:[1,0]
	v_pk_add_f32 v[28:29], v[28:29], 1.0 op_sel_hi:[1,0]
	v_pk_fma_f32 v[22:23], v[26:27], v[22:23], v[40:41]
	v_pk_fma_f32 v[24:25], v[28:29], v[24:25], v[42:43]
	v_cvt_pk_bf16_f32 v22, v22, v23
	s_nop 0
	v_cvt_pk_bf16_f32 v23, v24, v25
	global_store_dwordx2 v[30:31], v[22:23], off offset:1024
	v_mov_b64_e32 v[22:23], v[188:189]
	v_mov_b64_e32 v[24:25], v[190:191]
	s_nop 0
	v_mov_b64_e32 v[26:27], v[204:205]
	v_mov_b64_e32 v[28:29], v[206:207]
	v_pk_add_f32 v[22:23], v[22:23], 1.0 op_sel_hi:[1,0]
	v_pk_add_f32 v[24:25], v[24:25], 1.0 op_sel_hi:[1,0]
	v_pk_fma_f32 v[18:19], v[18:19], v[22:23], v[26:27]
	v_pk_fma_f32 v[20:21], v[20:21], v[24:25], v[28:29]
	v_cvt_pk_bf16_f32 v18, v18, v19
	s_nop 0
	v_cvt_pk_bf16_f32 v19, v20, v21
	global_store_dwordx2 v[30:31], v[18:19], off offset:1536
	s_andn2_b64 exec, exec, s[0:1]
	s_cbranch_execnz .LBB0_508
	s_branch .LBB0_7
